# c3 gla_load_vT: four V-chunk loads issued together into separate registers with counted vmcnt(3..0) instead of four serialized load-wait-write rounds
# baseline (speedup 1.0000x reference)
; __device__ __forceinline__ int ltid() { int t = threadIdx.x; asm volatile("" : "+v"(t)); return t; }
; __device__ __forceinline__ void gla_load_vT(const bf16_t* __restrict__ PC, int hd, int t0, unsigned char* sm) {
;     ...
;     const int tid = ltid(), j = tid >> 3, v0 = (tid & 7) * 32;
;     const bf16_t* vp = PC + (size_t)(t0 + j) * 3072 + 1024 + hd * 256 + v0;
; #pragma unroll
;     for (int i = 0; i < 4; ++i) {
;         const u32x4 w = *(const u32x4*)(vp + i * 8);
;         const int b = v0 + i * 8;
;         vT[(b + 0) * 72 + j] = (bf16_t)(w.x & 0xffff); vT[(b + 1) * 72 + j] = (bf16_t)(w.x >> 16);
;         vT[(b + 2) * 72 + j] = (bf16_t)(w.y & 0xffff); vT[(b + 3) * 72 + j] = (bf16_t)(w.y >> 16);
;         vT[(b + 4) * 72 + j] = (bf16_t)(w.z & 0xffff); vT[(b + 5) * 72 + j] = (bf16_t)(w.z >> 16);
;         vT[(b + 6) * 72 + j] = (bf16_t)(w.w & 0xffff); vT[(b + 7) * 72 + j] = (bf16_t)(w.w >> 16);
; __device__ __forceinline__ void gla_c3(const Args& a, int l, unsigned char* sm, const bf16_t* __restrict__ PC, const bf16_t* __restrict__ PLR, const bf16_t* __restrict__ UPD, bf16_t* __restrict__ OC) {
;     ...
;             for (int e = 0; e < 16; ++e) accO[mi][e] = 0.f;
;         for (int dir = 0; dir < 2; ++dir) {
;             const bf16_t* Sg = UPD + ((size_t)((dir * 4 + hd) * 256 + n)) * 32768;
;             bf16x8 sfr[8];
; #pragma unroll
;             for (int ks = 0; ks < 8; ++ks) sfr[ks] = *(const bf16x8*)(Sg + (32 * wid + r) * 128 + ks * 16 + 8 * h);
;             u32x4 qraw[2], kraw[2];
;             { const bf16_t* qp = PC + (size_t)(t0 + (tid >> 3)) * 3072 + hd * 128 + (tid & 7) * 16;
;               qraw[0] = *(const u32x4*)qp; qraw[1] = *(const u32x4*)(qp + 8); kraw[0] = *(const u32x4*)(qp + 512); kraw[1] = *(const u32x4*)(qp + 520); }
;             gla_b(a, l, hd, dir, t0, sm, PLR);
;             {
;                 const int j = tid >> 3, d0 = (tid & 7) * 16;
;                 float qv[16], kv[16];
;                 unpack8(qraw[0], qv); unpack8(qraw[1], qv + 8);
;                 unpack8(kraw[0], kv); unpack8(kraw[1], kv + 8);
;                 float qo[16], ko[16];
; #pragma unroll
;                 for (int e = 0; e < 16; ++e) { const float b = Gb[j * 129 + d0 + e]; qo[e] = qv[e] * 0.08838834764831845f * __expf(b); ko[e] = kv[e] * __expf(-b); }
.LBB0_454:
	v_mov_b32_e32 v0, v171
	s_lshl_b32 s2, s20, 6
	s_and_b32 s44, s2, 0x3fc0
	v_ashrrev_i32_e32 v2, 3, v0
	v_lshlrev_b32_e32 v0, 5, v0
	v_and_b32_e32 v3, 0xe0, v0
	v_add_u32_e32 v0, s44, v2
	v_mov_b64_e32 v[4:5], s[28:29]
	v_mad_i64_i32 v[0:1], s[2:3], v0, s6, v[4:5]
	s_and_b32 s2, s20, 0xffffff00
	s_ashr_i32 s3, s2, 31
	v_writelane_b32 v244, s2, 6
	v_lshlrev_b32_e32 v64, 1, v3
	v_lshlrev_b32_e32 v8, 1, v2
	v_lshl_add_u64 v[0:1], s[2:3], 1, v[0:1]
	v_lshl_add_u64 v[6:7], v[0:1], 0, v[64:65]
	v_mul_u32_u24_e32 v0, 0x48, v3
	v_lshlrev_b32_e32 v9, 1, v0
	global_load_dwordx4 v[0:3], v[6:7], off offset:2048
	global_load_dwordx4 v[204:207], v[6:7], off offset:2064
	global_load_dwordx4 v[208:211], v[6:7], off offset:2080
	global_load_dwordx4 v[212:215], v[6:7], off offset:2096
	v_writelane_b32 v244, s3, 7
	v_readlane_b32 s2, v248, 20
	v_mov_b32_e32 v91, v65
	v_readlane_b32 s64, v248, 61
	v_add3_u32 v10, s2, v8, v9
	v_add3_u32 v8, s2, v9, v8
	v_readlane_b32 s68, v247, 1
	v_readlane_b32 s69, v247, 2
	s_mov_b32 s46, s44
	s_mov_b32 s47, 0
	s_mov_b64 s[28:29], -1
	v_readlane_b32 s65, v248, 62
	v_readlane_b32 s66, v248, 63
	v_readlane_b32 s67, v247, 0
	v_readlane_b32 s70, v247, 3
	v_readlane_b32 s71, v247, 4
	v_readlane_b32 s72, v247, 5
	v_readlane_b32 s73, v247, 6
	v_readlane_b32 s74, v247, 7
	v_readlane_b32 s75, v247, 8
	v_readlane_b32 s76, v247, 9
	v_readlane_b32 s77, v247, 10
	v_readlane_b32 s78, v247, 11
	v_readlane_b32 s79, v247, 12
	s_waitcnt vmcnt(3)
	ds_write_b16 v10, v0
	ds_write_b16_d16_hi v8, v0 offset:144
	ds_write_b16 v8, v1 offset:288
	ds_write_b16_d16_hi v8, v1 offset:432
	ds_write_b16 v8, v2 offset:576
	ds_write_b16_d16_hi v8, v2 offset:720
	ds_write_b16 v8, v3 offset:864
	ds_write_b16_d16_hi v8, v3 offset:1008
	s_waitcnt vmcnt(2)
	ds_write_b16 v10, v204 offset:1152
	ds_write_b16_d16_hi v8, v204 offset:1296
	ds_write_b16 v8, v205 offset:1440
	ds_write_b16_d16_hi v8, v205 offset:1584
	ds_write_b16 v8, v206 offset:1728
	ds_write_b16_d16_hi v8, v206 offset:1872
	ds_write_b16 v8, v207 offset:2016
	ds_write_b16_d16_hi v8, v207 offset:2160
	s_waitcnt vmcnt(1)
	ds_write_b16 v10, v208 offset:2304
	ds_write_b16_d16_hi v8, v208 offset:2448
	ds_write_b16 v8, v209 offset:2592
	ds_write_b16_d16_hi v8, v209 offset:2736
	ds_write_b16 v8, v210 offset:2880
	ds_write_b16_d16_hi v8, v210 offset:3024
	ds_write_b16 v8, v211 offset:3168
	ds_write_b16_d16_hi v8, v211 offset:3312
	s_waitcnt vmcnt(0)
	ds_write_b16 v10, v212 offset:3456
	ds_write_b16_d16_hi v8, v212 offset:3600
	ds_write_b16 v8, v213 offset:3744
	ds_write_b16_d16_hi v8, v213 offset:3888
	ds_write_b16 v8, v214 offset:4032
	ds_write_b16_d16_hi v8, v214 offset:4176
	ds_write_b16 v8, v215 offset:4320
	ds_write_b16_d16_hi v8, v215 offset:4464
	v_add_u32_e32 v0, s44, v94
	v_mad_i64_i32 v[0:1], s[2:3], v0, s6, v[4:5]
	s_ashr_i32 s2, s20, 1
	s_and_b32 s26, s2, 0xffffff80
	s_ashr_i32 s27, s26, 31
	v_lshl_add_u64 v[0:1], s[26:27], 1, v[0:1]
	v_lshl_add_u64 v[12:13], v[0:1], 0, v[90:91]
	global_load_dwordx4 v[4:7], v[12:13], off offset:16
	global_load_dwordx4 v[8:11], v[12:13], off
	global_load_dwordx4 v[0:3], v[12:13], off offset:1040
	s_nop 0
	global_load_dwordx4 v[12:15], v[12:13], off offset:1024
	s_lshl_b64 s[2:3], s[26:27], 2
	s_add_u32 s27, s68, s2
	s_addc_u32 s45, s69, s3
	s_waitcnt vmcnt(3)
	v_lshlrev_b32_e32 v20, 16, v4
	s_waitcnt vmcnt(2)
	v_lshlrev_b32_e32 v16, 16, v8
	v_and_b32_e32 v8, 0xffff0000, v8
	v_lshlrev_b32_e32 v17, 16, v9
	v_and_b32_e32 v9, 0xffff0000, v9
	v_lshlrev_b32_e32 v18, 16, v10
	v_and_b32_e32 v10, 0xffff0000, v10
	v_lshlrev_b32_e32 v19, 16, v11
	v_and_b32_e32 v11, 0xffff0000, v11
	v_and_b32_e32 v4, 0xffff0000, v4
	v_lshlrev_b32_e32 v21, 16, v5
	v_and_b32_e32 v5, 0xffff0000, v5
	v_lshlrev_b32_e32 v22, 16, v6
	v_and_b32_e32 v6, 0xffff0000, v6
	v_lshlrev_b32_e32 v23, 16, v7
	v_and_b32_e32 v7, 0xffff0000, v7
	s_waitcnt vmcnt(1)
	v_lshlrev_b32_e32 v116, 16, v0
	v_and_b32_e32 v117, 0xffff0000, v0
	v_mov_b32_e32 v0, 0
	s_waitcnt vmcnt(0)
	v_lshlrev_b32_e32 v91, 16, v12
	v_and_b32_e32 v93, 0xffff0000, v12
	v_lshlrev_b32_e32 v110, 16, v13
	v_and_b32_e32 v111, 0xffff0000, v13
	v_lshlrev_b32_e32 v112, 16, v14
	v_and_b32_e32 v113, 0xffff0000, v14
	v_lshlrev_b32_e32 v114, 16, v15
	v_and_b32_e32 v115, 0xffff0000, v15
	v_lshlrev_b32_e32 v118, 16, v1
	v_and_b32_e32 v119, 0xffff0000, v1
	v_lshlrev_b32_e32 v120, 16, v2
	v_and_b32_e32 v121, 0xffff0000, v2
	v_lshlrev_b32_e32 v122, 16, v3
	v_and_b32_e32 v123, 0xffff0000, v3
	v_mul_f32_e32 v124, 0x3db504f3, v16
	v_mul_f32_e32 v125, 0x3db504f3, v8
	v_mul_f32_e32 v126, 0x3db504f3, v17
	v_mul_f32_e32 v127, 0x3db504f3, v9
	v_mul_f32_e32 v128, 0x3db504f3, v18
	v_mul_f32_e32 v129, 0x3db504f3, v10
	v_mul_f32_e32 v130, 0x3db504f3, v19
	v_mul_f32_e32 v131, 0x3db504f3, v11
	v_mul_f32_e32 v132, 0x3db504f3, v20
	v_mul_f32_e32 v133, 0x3db504f3, v4
	v_mul_f32_e32 v134, 0x3db504f3, v21
	v_mul_f32_e32 v135, 0x3db504f3, v5
	v_mul_f32_e32 v136, 0x3db504f3, v22
	v_mul_f32_e32 v137, 0x3db504f3, v6
	v_mul_f32_e32 v138, 0x3db504f3, v23
	v_mul_f32_e32 v139, 0x3db504f3, v7
	v_mov_b32_e32 v1, v0
	v_mov_b32_e32 v2, v0
	v_mov_b32_e32 v3, v0
	v_mov_b32_e32 v4, v0
	v_mov_b32_e32 v5, v0
	v_mov_b32_e32 v6, v0
	v_mov_b32_e32 v7, v0
	v_mov_b32_e32 v8, v0
	v_mov_b32_e32 v9, v0
	v_mov_b32_e32 v10, v0
	v_mov_b32_e32 v11, v0
	v_mov_b32_e32 v12, v0
	v_mov_b32_e32 v13, v0
	v_mov_b32_e32 v14, v0
	v_mov_b32_e32 v15, v0
	v_mov_b32_e32 v16, v0
	v_mov_b32_e32 v17, v0
	v_mov_b32_e32 v18, v0
	v_mov_b32_e32 v19, v0
	v_mov_b32_e32 v20, v0
	v_mov_b32_e32 v21, v0
	v_mov_b32_e32 v22, v0
	v_mov_b32_e32 v23, v0
	v_mov_b32_e32 v24, v0
	v_mov_b32_e32 v25, v0
	v_mov_b32_e32 v26, v0
	v_mov_b32_e32 v27, v0
	v_mov_b32_e32 v28, v0
	v_mov_b32_e32 v29, v0
	v_mov_b32_e32 v30, v0
	v_mov_b32_e32 v31, v0
	s_branch .LBB0_456
